# P5 conv: third-round prompt tasks on waves 0..3 of every workgroup, sample tasks on threads 256..415 of every workgroup (equal conv load per workgroup)
# speedup vs baseline: 1.0178x; 1.0178x over previous
.LBB0_980:
	v_readlane_b32 s36, v251, 0
	v_readlane_b32 s42, v251, 6
	v_readlane_b32 s43, v251, 7
	s_add_u32 s0, s42, 0x11114000
	s_addc_u32 s1, s43, 0
	v_readlane_b32 s37, v251, 1
	v_readlane_b32 s38, v251, 2
	v_readlane_b32 s39, v251, 3
	v_readlane_b32 s40, v251, 4
	v_readlane_b32 s41, v251, 5
	v_writelane_b32 v251, s0, 43
	v_lshlrev_b32_e32 v129, 3, v128
	s_nop 0
	v_writelane_b32 v251, s1, 44
	s_add_u32 s0, s42, 0x4154000
	s_addc_u32 s1, s43, 0
	v_writelane_b32 v251, s0, 45
	s_nop 1
	v_writelane_b32 v251, s1, 46
	s_mov_b32 s0, 0x50000
	v_cmp_gt_i32_e32 vcc, s0, v128
	v_readlane_b32 s0, v252, 32
	v_readlane_b32 s2, v252, 34
	v_readlane_b32 s12, v252, 44
	v_readlane_b32 s3, v252, 35
	v_readlane_b32 s13, v252, 45
	s_add_u32 s2, s12, 0x2800
	v_readlane_b32 s4, v252, 36
	s_addc_u32 s3, s13, 0
	v_readlane_b32 s5, v252, 37
	s_add_u32 s4, s12, 0x5000
	v_readlane_b32 s8, v252, 40
	s_addc_u32 s5, s13, 0
	v_readlane_b32 s9, v252, 41
	s_add_u32 s8, s12, 0x7800
	s_addc_u32 s9, s13, 0
	v_readlane_b32 s1, v252, 33
	s_add_u32 s0, s42, 0xee94000
	s_addc_u32 s1, s43, 0
	v_writelane_b32 v251, s0, 47
	v_readlane_b32 s10, v252, 42
	v_readlane_b32 s11, v252, 43
	v_writelane_b32 v251, s1, 48
	v_readlane_b32 s6, v252, 38
	v_readlane_b32 s7, v252, 39
	v_readlane_b32 s14, v252, 46
	v_readlane_b32 s15, v252, 47
	s_and_saveexec_b64 s[10:11], vcc
	s_cbranch_execz .LBB0_1003
	s_add_u32 s12, s40, 0x4820000
	s_addc_u32 s13, s41, 0
	v_and_b32_e32 v0, 1, v185
	s_add_u32 s14, s40, 0x4822800
	v_cmp_eq_u32_e64 s[6:7], 0, v0
	v_mov_b32_e32 v0, 0xfffff810
	s_addc_u32 s15, s41, 0
	v_cndmask_b32_e64 v116, v0, 0, s[6:7]
	v_mov_b32_e32 v0, 0x800
	v_mov_b32_e32 v121, 0
	s_add_u32 s16, s40, 0x4825000
	v_cndmask_b32_e64 v117, -1, 0, s[6:7]
	v_cndmask_b32_e64 v118, 16, v0, s[6:7]
	v_mov_b32_e32 v119, v121
	s_addc_u32 s17, s41, 0
	v_lshlrev_b32_e32 v195, 3, v128
	s_lshl_b32 s22, s34, 3
	v_lshlrev_b32_e32 v196, 10, v128
	s_lshl_b32 s23, s34, 10
	s_mov_b64 s[18:19], 0
	s_movk_i32 s24, 0x2600
	s_mov_b32 s25, 0xffff0000
	s_movk_i32 s26, 0x2800
	s_movk_i32 s27, 0xbf
	v_mbcnt_hi_u32_b32 v197, -1, v250
	v_mov_b32_e32 v198, v128
	s_mov_b32 s98, 0
	s_branch .LBB0_984

.LBB0_983:
	s_or_b64 exec, exec, s[0:1]
	v_add_u32_e32 v198, s34, v198
	v_add_u32_e32 v195, s22, v195
	v_add_u32_e32 v196, s23, v196
	s_add_i32 s98, s98, 1
	s_cmp_lg_u32 s98, 2
	s_cbranch_scc1 .Lcv_a
	v_lshrrev_b32_e32 v198, 9, v128
	v_lshl_add_u32 v198, v198, 8, v185
	v_add_u32_e32 v198, 0x40000, v198
	v_cmp_gt_u32_e32 vcc, 0x100, v185
	v_cndmask_b32_e32 v198, 4.0, v198, vcc
	v_lshlrev_b32_e32 v195, 3, v198
	v_lshlrev_b32_e32 v196, 10, v198
.Lcv_a:
	s_mov_b32 s0, 0x4ffff
	v_cmp_lt_i32_e32 vcc, s0, v198
	s_or_b64 s[18:19], vcc, s[18:19]
	s_andn2_b64 exec, exec, s[18:19]
	s_cbranch_execz .LBB0_1003

.LBB0_1003:
	s_or_b64 exec, exec, s[10:11]
	s_add_u32 s36, s42, 0x10f94000
	s_mov_b32 s0, 0xa000
	s_addc_u32 s37, s43, 0
	v_lshrrev_b32_e32 v128, 9, v128
	v_mul_u32_u24_e32 v128, 0xa0, v128
	v_add_u32_e32 v129, 0xffffff00, v185
	v_cmp_gt_u32_e32 vcc, 0xa0, v129
	v_add_u32_e32 v128, v128, v129
	v_cndmask_b32_e32 v128, 4.0, v128, vcc
	v_lshlrev_b32_e32 v129, 3, v128
	v_cmp_gt_u32_e32 vcc, s0, v128
	s_and_saveexec_b64 s[0:1], vcc
	s_cbranch_execz .LBB0_1022
	s_add_u32 s6, s40, 0xaa5c000
	s_addc_u32 s7, s41, 0
	s_add_u32 s10, s40, 0xaa5e800
	s_addc_u32 s11, s41, 0
	s_add_u32 s12, s40, 0xaa61000
	s_addc_u32 s13, s41, 0
	s_lshl_b32 s18, s34, 3
	s_mov_b64 s[14:15], 0
	s_movk_i32 s19, 0x2600
	v_mov_b64_e32 v[80:81], s[76:77]
	s_movk_i32 s20, 0x1000
	s_movk_i32 s21, 0x2800
	v_mov_b64_e32 v[82:83], s[46:47]
	v_mov_b32_e32 v85, 0
	s_movk_i32 s22, 0xc00
	s_branch .LBB0_1006
